# adds GLA heads' K/V/decay chunk loads issued up front (heads 1,2 in the prologue, head 3 two heads ahead) with counted waits
# baseline (speedup 1.0000x reference)
; DI void kv_chunk(CP p, int b, int n, LAS unsigned char* lds) {
;     ...
;         u32x4 gv0, gv1, gk; f32x4 c0, c1, e0, e1;
;         const float* bcb = (const float*)(p->ws + WS_BCUM) + (size_t)tok0 * 256;
;     ...
;         KVG_LOAD(0);
.LBB0_305:
	s_add_i32 s100, s64, -32
	s_mov_b32 s101, 0
	s_lshl_b64 s[100:101], s[100:101], 15
	v_lshl_add_u64 v[70:71], v[68:69], 0, s[100:101]
	s_mov_b64 s[100:101], 0x2000
	v_lshl_add_u64 v[88:89], v[70:71], 0, s[100:101]
	v_lshl_add_u64 v[90:91], v[88:89], 0, s[100:101]
	v_lshl_add_u64 v[92:93], v[90:91], 0, s[100:101]
	ds_read_b128 v[72:75], v65
	ds_read_b128 v[76:79], v65 offset:8704
	ds_read_b128 v[80:83], v65 offset:17408
	ds_read_b128 v[84:87], v65 offset:26112
	s_waitcnt lgkmcnt(3)
	global_store_dwordx4 v[70:71], v[72:75], off
	s_waitcnt lgkmcnt(2)
	global_store_dwordx4 v[88:89], v[76:79], off
	s_waitcnt lgkmcnt(1)
	global_store_dwordx4 v[90:91], v[80:83], off
	s_waitcnt lgkmcnt(0)
	global_store_dwordx4 v[92:93], v[84:87], off
	s_or_b32 s52, s56, s55
	s_lshl_b64 s[48:49], s[48:49], 10
	v_readlane_b32 s53, v254, 40
	s_add_u32 s56, s53, s48
	v_readlane_b32 s48, v254, 41
	s_waitcnt vmcnt(9)
	v_lshlrev_b32_e32 v8, 1, v18
	v_mov_b32_e32 v9, v197
	s_addc_u32 s57, s48, s49
	v_lshl_add_u64 v[8:9], s[50:51], 0, v[8:9]
	s_add_u32 s48, s50, 0x2c00
	v_lshl_add_u64 v[38:39], v[16:17], 1, v[8:9]
	s_addc_u32 s49, s51, 0
	v_lshl_add_u64 v[36:37], v[16:17], 2, s[56:57]
	v_add_co_u32_e32 v8, vcc, s33, v38
	s_mov_b64 s[50:51], 0xfc00
	s_nop 0
	v_addc_co_u32_e32 v9, vcc, 0, v39, vcc
	v_lshl_add_u64 v[24:25], v[36:37], 0, s[50:51]
	s_mov_b32 s50, 0xf000
	v_lshl_add_u64 v[0:1], v[28:29], 1, s[48:49]
	v_lshlrev_b32_e32 v196, 1, v20
	v_lshl_add_u64 v[2:3], v[30:31], 1, s[48:49]
	v_lshlrev_b32_e32 v10, 10, v32
	v_mov_b32_e32 v11, v197
	v_add_co_u32_e32 v16, vcc, s50, v36
	v_lshl_add_u64 v[0:1], v[0:1], 0, v[196:197]
	v_lshl_add_u64 v[4:5], v[2:3], 0, v[196:197]
	v_lshl_add_u64 v[20:21], v[36:37], 0, v[10:11]
	v_addc_co_u32_e32 v17, vcc, 0, v37, vcc
	global_load_dwordx4 v[0:3], v[0:1], off
	s_nop 0
	global_load_dwordx4 v[4:7], v[4:5], off
	s_nop 0
	global_load_dwordx4 v[8:11], v[8:9], off offset:2560
	s_nop 0
	global_load_dwordx4 v[12:15], v[20:21], off
	s_nop 0
	global_load_dwordx4 v[16:19], v[16:17], off offset:3072
	s_nop 0
	global_load_dwordx4 v[20:23], v[20:21], off offset:16
	s_nop 0
	global_load_dwordx4 v[24:27], v[24:25], off offset:16
	s_and_b32 s53, s60, 48
	s_mov_b64 s[50:51], 0x2a00
	v_lshlrev_b32_e32 v46, 8, v32
	v_or_b32_e32 v32, s53, v44
	s_movk_i32 s55, 0x90
	v_lshl_add_u64 v[38:39], v[38:39], 0, s[50:51]
	s_and_b32 s51, s22, -4
	v_mad_u32_u24 v51, v32, s55, 0
	s_lshl_b32 s53, s53, 1
	v_readlane_b32 s55, v254, 63
	s_add_u32 s56, s55, s53
	v_readlane_b32 s53, v255, 0
	s_addc_u32 s57, s53, 0
	s_or_b32 s53, s51, 1
	s_or_b32 s55, s51, 2
	s_or_b32 s22, s22, 3
	v_lshlrev_b32_e32 v32, 1, v34
	v_lshl_or_b32 v34, s51, 4, v44
	v_lshl_or_b32 v40, s53, 4, v44
	v_lshl_or_b32 v42, s55, 4, v44
	v_lshl_or_b32 v44, s22, 4, v44
	v_mov_b32_e32 v33, v197
	v_lshl_add_u32 v52, s51, 5, v35
	v_lshl_add_u32 v53, s53, 5, v35
	v_lshl_add_u32 v54, s55, 5, v35
	v_lshl_add_u32 v55, s22, 5, v35
	v_ashrrev_i32_e32 v35, 31, v34
	v_ashrrev_i32_e32 v41, 31, v40
	v_ashrrev_i32_e32 v43, 31, v42
	v_ashrrev_i32_e32 v45, 31, v44
	s_mov_b32 s50, 0
	v_lshl_add_u64 v[32:33], s[56:57], 0, v[32:33]
	v_lshlrev_b64 v[34:35], 7, v[34:35]
	v_lshlrev_b64 v[40:41], 7, v[40:41]
	v_lshlrev_b64 v[42:43], 7, v[42:43]
	v_lshlrev_b64 v[44:45], 7, v[44:45]
	v_lshlrev_b32_e32 v46, 2, v46
	v_add_u32_e32 v51, v51, v47
	v_add_u32_e32 v52, v52, v50
	v_add_u32_e32 v53, v53, v50
	v_add_u32_e32 v54, v54, v50
	v_add_u32_e32 v50, v55, v50
	v_readlane_b32 s65, v253, 53
	s_mov_b32 s100, 0x100
	s_add_u32 s100, s48, s100
	s_addc_u32 s101, s49, 0
	v_lshl_add_u64 v[94:95], v[28:29], 1, s[100:101]
	v_lshl_add_u64 v[96:97], v[30:31], 1, s[100:101]
	s_mov_b32 s100, 0x40
	s_mov_b32 s101, 0
	v_lshl_add_u64 v[110:111], s[100:101], 2, v[36:37]
	v_mov_b32_e32 v47, v197
	v_lshl_add_u64 v[114:115], v[110:111], 0, v[46:47]
	s_mov_b32 s100, 0xfc00
	v_lshl_add_u64 v[118:119], v[110:111], 0, s[100:101]
	s_mov_b32 s100, 0xf000
	v_lshl_add_u64 v[110:111], v[110:111], 0, s[100:101]
	v_lshl_add_u64 v[94:95], v[94:95], 0, v[196:197]
	v_lshl_add_u64 v[98:99], v[96:97], 0, v[196:197]
	s_mov_b32 s100, 0x80
	v_lshl_add_u64 v[102:103], v[38:39], 0, s[100:101]
	global_load_dwordx4 v[94:97], v[94:95], off
	global_load_dwordx4 v[98:101], v[98:99], off
	global_load_dwordx4 v[102:105], v[102:103], off
	global_load_dwordx4 v[106:109], v[114:115], off
	global_load_dwordx4 v[110:113], v[110:111], off offset:3072
	global_load_dwordx4 v[114:117], v[114:115], off offset:16
	global_load_dwordx4 v[118:121], v[118:119], off offset:16
	s_mov_b32 s100, 0x200
	s_add_u32 s100, s48, s100
	s_addc_u32 s101, s49, 0
	v_lshl_add_u64 v[122:123], v[28:29], 1, s[100:101]
	v_lshl_add_u64 v[124:125], v[30:31], 1, s[100:101]
	s_mov_b32 s100, 0x80
	s_mov_b32 s101, 0
	v_lshl_add_u64 v[138:139], s[100:101], 2, v[36:37]
	v_mov_b32_e32 v47, v197
	v_lshl_add_u64 v[70:71], v[138:139], 0, v[46:47]
	s_mov_b32 s100, 0xfc00
	v_lshl_add_u64 v[74:75], v[138:139], 0, s[100:101]
	s_mov_b32 s100, 0xf000
	v_lshl_add_u64 v[138:139], v[138:139], 0, s[100:101]
	v_lshl_add_u64 v[122:123], v[122:123], 0, v[196:197]
	v_lshl_add_u64 v[126:127], v[124:125], 0, v[196:197]
	s_mov_b32 s100, 0x100
	v_lshl_add_u64 v[130:131], v[38:39], 0, s[100:101]
	global_load_dwordx4 v[122:125], v[122:123], off
	global_load_dwordx4 v[126:129], v[126:127], off
	global_load_dwordx4 v[130:133], v[130:131], off
	global_load_dwordx4 v[134:137], v[70:71], off
	global_load_dwordx4 v[138:141], v[138:139], off offset:3072
	global_load_dwordx4 v[70:73], v[70:71], off offset:16
	global_load_dwordx4 v[74:77], v[74:75], off offset:16
	s_branch .LBB0_307

; #define LAS __attribute__((address_space(3)))
; DI unsigned pk2(float lo, float hi) { f32x2_t v = {lo, hi}; bf16x2_t b = __builtin_convertvector(v, bf16x2_t); return __builtin_bit_cast(unsigned, b); }
; DI void unpack8(const u32x4 w, float (&f)[8]) { f[0] = bflo(w.x); f[1] = bfhi(w.x); f[2] = bflo(w.y); f[3] = bfhi(w.y); f[4] = bflo(w.z); f[5] = bfhi(w.z); f[6] = bflo(w.w); f[7] = bfhi(w.w); }
; DI void kv_chunk(CP p, int b, int n, LAS unsigned char* lds) {
;     ...
;         KVG_LOAD(0);
; #pragma unroll 1
;         for (int h = 0; h < 4; ++h) {
;             *(LAS u32x4*)(lds + VT + (tid >> 4) * 272 + (tid & 15) * 16) = gv0; *(LAS u32x4*)(lds + VT + (32 + (tid >> 4)) * 272 + (tid & 15) * 16) = gv1;
;             { float x[8]; unpack8(gk, x);
;               const float wd[8] = {e0.x - c0.x, e0.y - c0.y, e0.z - c0.z, e0.w - c0.w, e1.x - c1.x, e1.y - c1.y, e1.z - c1.z, e1.w - c1.w};
; #pragma unroll
;               for (int e = 0; e < 8; ++e) *(LAS bf16*)(lds + KT + (kpt * 8 + e) * 144 + kj * 2) = (bf16)(pk2(x[e] * __expf(wd[e]), 0.f) & 0xffffu); }
;             if (h < 3) KVG_LOAD(h + 1);
.LBB0_307:
	s_cmp_eq_u32 s50, 0
	s_cbranch_scc1 .Lgp_h0
	s_cmp_eq_u32 s50, 1
	s_cbranch_scc1 .Lgp_h1
	s_cmp_eq_u32 s50, 2
	s_cbranch_scc1 .Lgp_h2
	s_waitcnt vmcnt(8)
	v_mov_b32_e32 v0, v94
	v_mov_b32_e32 v1, v95
	v_mov_b32_e32 v2, v96
	v_mov_b32_e32 v3, v97
	v_mov_b32_e32 v4, v98
	v_mov_b32_e32 v5, v99
	v_mov_b32_e32 v6, v100
	v_mov_b32_e32 v7, v101
	v_mov_b32_e32 v8, v102
	v_mov_b32_e32 v9, v103
	v_mov_b32_e32 v10, v104
	v_mov_b32_e32 v11, v105
	v_mov_b32_e32 v12, v106
	v_mov_b32_e32 v13, v107
	v_mov_b32_e32 v14, v108
	v_mov_b32_e32 v15, v109
	v_mov_b32_e32 v16, v110
	v_mov_b32_e32 v17, v111
	v_mov_b32_e32 v18, v112
	v_mov_b32_e32 v19, v113
	v_mov_b32_e32 v20, v114
	v_mov_b32_e32 v21, v115
	v_mov_b32_e32 v22, v116
	v_mov_b32_e32 v23, v117
	v_mov_b32_e32 v24, v118
	v_mov_b32_e32 v25, v119
	v_mov_b32_e32 v26, v120
	v_mov_b32_e32 v27, v121
	s_branch .Lgp_go
.Lgp_h2:
	s_waitcnt vmcnt(15)
	v_mov_b32_e32 v0, v122
	v_mov_b32_e32 v1, v123
	v_mov_b32_e32 v2, v124
	v_mov_b32_e32 v3, v125
	v_mov_b32_e32 v4, v126
	v_mov_b32_e32 v5, v127
	v_mov_b32_e32 v6, v128
	v_mov_b32_e32 v7, v129
	v_mov_b32_e32 v8, v130
	v_mov_b32_e32 v9, v131
	v_mov_b32_e32 v10, v132
	v_mov_b32_e32 v11, v133
	v_mov_b32_e32 v12, v134
	v_mov_b32_e32 v13, v135
	v_mov_b32_e32 v14, v136
	v_mov_b32_e32 v15, v137
	v_mov_b32_e32 v16, v138
	v_mov_b32_e32 v17, v139
	v_mov_b32_e32 v18, v140
	v_mov_b32_e32 v19, v141
	v_mov_b32_e32 v20, v70
	v_mov_b32_e32 v21, v71
	v_mov_b32_e32 v22, v72
	v_mov_b32_e32 v23, v73
	v_mov_b32_e32 v24, v74
	v_mov_b32_e32 v25, v75
	v_mov_b32_e32 v26, v76
	v_mov_b32_e32 v27, v77
	s_branch .Lgp_go
.Lgp_h1:
	s_waitcnt vmcnt(11)
	v_mov_b32_e32 v0, v94
	v_mov_b32_e32 v1, v95
	v_mov_b32_e32 v2, v96
	v_mov_b32_e32 v3, v97
	v_mov_b32_e32 v4, v98
	v_mov_b32_e32 v5, v99
	v_mov_b32_e32 v6, v100
	v_mov_b32_e32 v7, v101
	v_mov_b32_e32 v8, v102
	v_mov_b32_e32 v9, v103
	v_mov_b32_e32 v10, v104
	v_mov_b32_e32 v11, v105
	v_mov_b32_e32 v12, v106
	v_mov_b32_e32 v13, v107
	v_mov_b32_e32 v14, v108
	v_mov_b32_e32 v15, v109
	v_mov_b32_e32 v16, v110
	v_mov_b32_e32 v17, v111
	v_mov_b32_e32 v18, v112
	v_mov_b32_e32 v19, v113
	v_mov_b32_e32 v20, v114
	v_mov_b32_e32 v21, v115
	v_mov_b32_e32 v22, v116
	v_mov_b32_e32 v23, v117
	v_mov_b32_e32 v24, v118
	v_mov_b32_e32 v25, v119
	v_mov_b32_e32 v26, v120
	v_mov_b32_e32 v27, v121
	s_branch .Lgp_go
.Lgp_h0:
	s_waitcnt vmcnt(16)
.Lgp_go:
	v_sub_f32_e32 v62, v16, v12
	v_mul_f32_e32 v62, 0x3fb8aa3b, v62
	v_sub_f32_e32 v63, v17, v13
	v_exp_f32_e32 v62, v62
	v_mul_f32_e32 v63, 0x3fb8aa3b, v63
	v_exp_f32_e32 v63, v63
	v_lshlrev_b32_e32 v47, 16, v8
	v_mul_f32_e32 v47, v62, v47
	v_and_b32_e32 v55, 0xffff0000, v8
	v_cvt_pk_bf16_f32 v47, v47, s0
	ds_write_b128 v48, v[0:3]
	ds_write_b128 v48, v[4:7] offset:8704
	ds_write_b16 v49, v47 offset:18432
	v_mul_f32_e32 v47, v63, v55
	v_sub_f32_e32 v143, v18, v14
	v_sub_f32_e32 v145, v19, v15
	v_cvt_pk_bf16_f32 v47, v47, s0
	v_mul_f32_e32 v55, 0x3fb8aa3b, v143
	ds_write_b16 v49, v47 offset:18576
	v_mul_f32_e32 v47, 0x3fb8aa3b, v145
	v_exp_f32_e32 v55, v55
	v_exp_f32_e32 v47, v47
	v_lshlrev_b32_e32 v56, 16, v9
	v_and_b32_e32 v57, 0xffff0000, v9
	v_mul_f32_e32 v55, v55, v56
	v_mul_f32_e32 v47, v47, v57
	s_cmp_eq_u32 s50, 0
	s_cbranch_scc0 .Lgp_w2
	s_waitcnt vmcnt(14)
.Lgp_w2:
	v_sub_f32_e32 v147, v24, v20
	v_sub_f32_e32 v149, v25, v21
	v_cvt_pk_bf16_f32 v55, v55, s0
	v_cvt_pk_bf16_f32 v47, v47, s0
	ds_write_b16 v49, v55 offset:18720
	v_mul_f32_e32 v55, 0x3fb8aa3b, v147
	ds_write_b16 v49, v47 offset:18864
	v_mul_f32_e32 v47, 0x3fb8aa3b, v149
	v_exp_f32_e32 v55, v55
	v_exp_f32_e32 v47, v47
	v_lshlrev_b32_e32 v58, 16, v10
	v_and_b32_e32 v59, 0xffff0000, v10
	v_mul_f32_e32 v55, v55, v58
	v_mul_f32_e32 v47, v47, v59
	v_sub_f32_e32 v151, v26, v22
	v_sub_f32_e32 v153, v27, v23
	v_cvt_pk_bf16_f32 v55, v55, s0
	v_cvt_pk_bf16_f32 v47, v47, s0
	ds_write_b16 v49, v55 offset:19008
	v_mul_f32_e32 v55, 0x3fb8aa3b, v151
	ds_write_b16 v49, v47 offset:19152
	v_mul_f32_e32 v47, 0x3fb8aa3b, v153
	v_exp_f32_e32 v55, v55
	v_exp_f32_e32 v47, v47
	v_lshlrev_b32_e32 v60, 16, v11
	v_and_b32_e32 v61, 0xffff0000, v11
	v_mul_f32_e32 v55, v55, v60
	v_mul_f32_e32 v47, v47, v61
	v_cvt_pk_bf16_f32 v55, v55, s0
	v_cvt_pk_bf16_f32 v47, v47, s0
	s_add_i32 s51, s50, 1
	s_cmp_lg_u32 s50, 1
	ds_write_b16 v49, v55 offset:19296
	ds_write_b16 v49, v47 offset:19440
	s_cbranch_scc1 .LBB0_306
	s_mov_b32 s100, 0x300
	s_add_u32 s100, s48, s100
	s_addc_u32 s101, s49, 0
	v_lshl_add_u64 v[94:95], v[28:29], 1, s[100:101]
	v_lshl_add_u64 v[96:97], v[30:31], 1, s[100:101]
	s_mov_b32 s100, 0xc0
	s_mov_b32 s101, 0
	v_lshl_add_u64 v[110:111], s[100:101], 2, v[36:37]
	v_mov_b32_e32 v47, v197
	v_lshl_add_u64 v[114:115], v[110:111], 0, v[46:47]
	s_mov_b32 s100, 0xfc00
	v_lshl_add_u64 v[118:119], v[110:111], 0, s[100:101]
	s_mov_b32 s100, 0xf000
	v_lshl_add_u64 v[110:111], v[110:111], 0, s[100:101]
	v_lshl_add_u64 v[94:95], v[94:95], 0, v[196:197]
	v_lshl_add_u64 v[98:99], v[96:97], 0, v[196:197]
	s_mov_b32 s100, 0x180
	v_lshl_add_u64 v[102:103], v[38:39], 0, s[100:101]
	global_load_dwordx4 v[94:97], v[94:95], off
	global_load_dwordx4 v[98:101], v[98:99], off
	global_load_dwordx4 v[102:105], v[102:103], off
	global_load_dwordx4 v[106:109], v[114:115], off
	global_load_dwordx4 v[110:113], v[110:111], off offset:3072
	global_load_dwordx4 v[114:117], v[114:115], off offset:16
	global_load_dwordx4 v[118:121], v[118:119], off offset:16
	s_branch .LBB0_306
